# Gray MFMA order + post-MFMA barrier issued before the last MFMA of each block
# speedup vs baseline: 1.0194x; 1.0011x over previous
; #define PG8_STAGE(bufoff, gbase, voff) do { _Pragma("unroll") for (int _i = 0; _i < 2; ++_i) \
;         __builtin_amdgcn_global_load_lds((const unsigned*)((const char*)(gbase) + (voff)[_i]), (PG8_LAS unsigned*)(lds + (bufoff) + ldsw + _i * 8192), 16, 0, 0); } while (0)
; #define PG8_LDA(dst, b, h) do { _Pragma("unroll") for (int m = 0; m < 4; ++m) _Pragma("unroll") for (int k = 0; k < 2; ++k) dst[m][k] = *(const PG8_LAS bf16x8*)(lds + PG8_SA(b, h) + aoff + m * 2048 + k * 1024); } while (0)
; #define PG8_LDB(dst, b, h) do { _Pragma("unroll") for (int n = 0; n < 2; ++n) _Pragma("unroll") for (int k = 0; k < 2; ++k) dst[n][k] = *(const PG8_LAS bf16x8*)(lds + PG8_SB(b, h) + boff + n * 2048 + k * 1024); } while (0)
; #define PG8_MMA(ai, bj, At, Bt) do { __builtin_amdgcn_s_setprio(1); _Pragma("unroll") for (int m = 0; m < 4; ++m) _Pragma("unroll") for (int n = 0; n < 2; ++n) _Pragma("unroll") for (int k = 0; k < 2; ++k) \
;         acc[ai][bj][m][n] = __builtin_amdgcn_mfma_f32_16x16x32_bf16(Bt[n][k], At[m][k], acc[ai][bj][m][n], 0, 0, 0); __builtin_amdgcn_s_setprio(0); } while (0)
; #define PG8_WAIT_V(n) asm volatile("s_waitcnt vmcnt(" #n ")" ::: "memory")
; #define PG8_WAIT_L(n) asm volatile("s_waitcnt lgkmcnt(" #n ")" ::: "memory")
; template <class Epi, class Sched, bool ALIGN_EPI = false, bool SP2 = false>
; __device__ __forceinline__ void gemm_phase(PG8_LAS unsigned char* lds, const Gemm g, const Sched& S, const Epi& E) {
;     ...
;             const bool last = (t == nt - 2);
;             const char* a1 = cA + (size_t)(t + 1) * kstepA;
;             const char* a2 = last ? nA : cA + (size_t)(t + 2) * kstepA; const char* b2 = last ? nB : cB + (size_t)(t + 2) * kstep;
;             const char* a3 = a2 + kstepA; const char* b3 = b2 + kstep;
;             if (last && has_next) S.a_ready(nxt);
;             if constexpr (SP2) {
;             PG8_LDB(B0, 0, 0); PG8_LDB(B1, 0, 1); PG8_SCHED; PG8_LDA(At, 0, 0); PG8_STAGE(PG8_SA(1, 1), a1 + hstep, voffA);
;             PG8_WAIT_V(8); PG8_WAIT_L(0); PG8_BAR; PG8_MMA(0, 0, At, B0); PG8_MMA(0, 1, At, B1); PG8_BAR; PG8_SCHED;
;             PG8_LDA(At, 0, 1); PG8_STAGE(PG8_SB(0, 0), b2, voffB); PG8_STAGE(PG8_SB(0, 1), b2 + hstep, voffB); PG8_STAGE(PG8_SA(0, 0), a2, voffA);
;             PG8_WAIT_V(8); PG8_WAIT_L(0); PG8_BAR; PG8_MMA(1, 0, At, B0); PG8_MMA(1, 1, At, B1); PG8_BAR; PG8_SCHED;
.LBB0_238:
	s_add_u32 s2, s24, 0x8000
	s_addc_u32 s3, s25, 0
	s_cmp_eq_u32 s71, 12
	s_cselect_b32 s46, s67, s2
	s_cselect_b32 s47, s11, s3
	s_cselect_b32 s42, s68, s69
	s_cselect_b32 s43, s9, s70
	s_add_u32 s26, s46, 0x4000
	s_addc_u32 s27, s47, 0
	v_add_u32_e32 v148, s76, v150
	s_add_i32 s72, 0, 0x14000
	ds_read_b128 v[144:147], v148
	ds_read_b128 v[160:163], v148 offset:1024
	ds_read_b128 v[164:167], v148 offset:2048
	ds_read_b128 v[168:171], v148 offset:3072
	v_add_u32_e32 v148, s72, v150
	ds_read_b128 v[172:175], v148
	ds_read_b128 v[176:179], v148 offset:1024
	ds_read_b128 v[180:183], v148 offset:2048
	ds_read_b128 v[184:187], v148 offset:3072
	v_lshl_add_u64 v[148:149], s[24:25], 0, v[142:143]
	s_add_i32 m0, s23, 0xc000
	ds_read_b128 v[188:191], v152
	ds_read_b128 v[206:209], v152 offset:1024
	ds_read_b128 v[210:213], v152 offset:2048
	ds_read_b128 v[214:217], v152 offset:3072
	ds_read_b128 v[218:221], v152 offset:4096
	ds_read_b128 v[222:225], v152 offset:5120
	ds_read_b128 v[226:229], v152 offset:6144
	ds_read_b128 v[230:233], v152 offset:7168
	global_load_lds_dwordx4 v[148:149], off
	v_lshl_add_u64 v[148:149], s[24:25], 0, v[140:141]
	s_add_i32 m0, s23, 0xe000
	s_nop 0
	global_load_lds_dwordx4 v[148:149], off
	s_waitcnt vmcnt(8)
	s_waitcnt lgkmcnt(0)
	s_barrier
	s_setprio 1
	s_waitcnt lgkmcnt(0)
	v_mfma_f32_16x16x32_bf16 v[126:129], v[144:147], v[188:191], v[126:129]
	v_mfma_f32_16x16x32_bf16 v[126:129], v[160:163], v[206:209], v[126:129]
	v_mfma_f32_16x16x32_bf16 v[122:125], v[168:171], v[206:209], v[122:125]
	v_mfma_f32_16x16x32_bf16 v[122:125], v[164:167], v[188:191], v[122:125]
	v_mfma_f32_16x16x32_bf16 v[106:109], v[164:167], v[210:213], v[106:109]
	v_mfma_f32_16x16x32_bf16 v[106:109], v[168:171], v[214:217], v[106:109]
	v_mfma_f32_16x16x32_bf16 v[110:113], v[160:163], v[214:217], v[110:113]
	v_mfma_f32_16x16x32_bf16 v[110:113], v[144:147], v[210:213], v[110:113]
	v_mfma_f32_16x16x32_bf16 v[94:97], v[144:147], v[218:221], v[94:97]
	v_mfma_f32_16x16x32_bf16 v[94:97], v[160:163], v[222:225], v[94:97]
	v_mfma_f32_16x16x32_bf16 v[90:93], v[168:171], v[222:225], v[90:93]
	v_mfma_f32_16x16x32_bf16 v[90:93], v[164:167], v[218:221], v[90:93]
	v_mfma_f32_16x16x32_bf16 v[74:77], v[164:167], v[226:229], v[74:77]
	v_mfma_f32_16x16x32_bf16 v[74:77], v[168:171], v[230:233], v[74:77]
	v_mfma_f32_16x16x32_bf16 v[78:81], v[160:163], v[230:233], v[78:81]
	v_mfma_f32_16x16x32_bf16 v[78:81], v[144:147], v[226:229], v[78:81]
	s_setprio 0
	s_setprio 1
	v_mfma_f32_16x16x32_bf16 v[118:121], v[172:175], v[188:191], v[118:121]
	v_mfma_f32_16x16x32_bf16 v[118:121], v[176:179], v[206:209], v[118:121]
	v_mfma_f32_16x16x32_bf16 v[114:117], v[184:187], v[206:209], v[114:117]
	v_mfma_f32_16x16x32_bf16 v[114:117], v[180:183], v[188:191], v[114:117]
	v_mfma_f32_16x16x32_bf16 v[98:101], v[180:183], v[210:213], v[98:101]
	v_mfma_f32_16x16x32_bf16 v[98:101], v[184:187], v[214:217], v[98:101]
	v_mfma_f32_16x16x32_bf16 v[102:105], v[176:179], v[214:217], v[102:105]
	v_mfma_f32_16x16x32_bf16 v[102:105], v[172:175], v[210:213], v[102:105]
	v_mfma_f32_16x16x32_bf16 v[86:89], v[172:175], v[218:221], v[86:89]
	v_mfma_f32_16x16x32_bf16 v[86:89], v[176:179], v[222:225], v[86:89]
	v_mfma_f32_16x16x32_bf16 v[82:85], v[184:187], v[222:225], v[82:85]
	v_mfma_f32_16x16x32_bf16 v[82:85], v[180:183], v[218:221], v[82:85]
	v_mfma_f32_16x16x32_bf16 v[66:69], v[180:183], v[226:229], v[66:69]
	v_mfma_f32_16x16x32_bf16 v[66:69], v[184:187], v[230:233], v[66:69]
	v_mfma_f32_16x16x32_bf16 v[70:73], v[176:179], v[230:233], v[70:73]
	s_barrier
	v_mfma_f32_16x16x32_bf16 v[70:73], v[172:175], v[226:229], v[70:73]
	s_setprio 0
	s_add_i32 s24, s76, s51
	v_lshl_add_u64 v[148:149], s[42:43], 0, v[132:133]
	s_mov_b32 m0, s24
	ds_read_b128 v[188:191], v152 offset:16384
	ds_read_b128 v[206:209], v152 offset:17408
	ds_read_b128 v[210:213], v152 offset:18432
	ds_read_b128 v[214:217], v152 offset:19456
	ds_read_b128 v[218:221], v152 offset:20480
	ds_read_b128 v[222:225], v152 offset:21504
	ds_read_b128 v[226:229], v152 offset:22528
	ds_read_b128 v[230:233], v152 offset:23552
	global_load_lds_dwordx4 v[148:149], off
	s_add_i32 m0, s24, 0x2000
	s_add_u32 s24, s42, 0x40000
	v_lshl_add_u64 v[234:235], s[42:43], 0, v[136:137]
	s_addc_u32 s25, s43, 0
	s_add_i32 s72, s72, s51
	global_load_lds_dwordx4 v[234:235], off
	v_lshl_add_u64 v[236:237], s[24:25], 0, v[132:133]
	s_mov_b32 m0, s72
	s_nop 0
	global_load_lds_dwordx4 v[236:237], off
	v_lshl_add_u64 v[236:237], s[24:25], 0, v[136:137]
	s_add_i32 m0, s72, 0x2000
	s_nop 0
	global_load_lds_dwordx4 v[236:237], off
	v_lshl_add_u64 v[236:237], s[46:47], 0, v[130:131]
	s_mov_b32 m0, s23
	s_nop 0
	global_load_lds_dwordx4 v[236:237], off
	v_lshl_add_u64 v[236:237], s[46:47], 0, v[134:135]
	s_mov_b32 m0, s56
	s_nop 0
	global_load_lds_dwordx4 v[236:237], off
	s_waitcnt vmcnt(8)
	s_waitcnt lgkmcnt(0)
	s_barrier
; #define PG8_STAGE(bufoff, gbase, voff) do { _Pragma("unroll") for (int _i = 0; _i < 2; ++_i) \
;         __builtin_amdgcn_global_load_lds((const unsigned*)((const char*)(gbase) + (voff)[_i]), (PG8_LAS unsigned*)(lds + (bufoff) + ldsw + _i * 8192), 16, 0, 0); } while (0)
; #define PG8_LDA(dst, b, h) do { _Pragma("unroll") for (int m = 0; m < 4; ++m) _Pragma("unroll") for (int k = 0; k < 2; ++k) dst[m][k] = *(const PG8_LAS bf16x8*)(lds + PG8_SA(b, h) + aoff + m * 2048 + k * 1024); } while (0)
; #define PG8_LDB(dst, b, h) do { _Pragma("unroll") for (int n = 0; n < 2; ++n) _Pragma("unroll") for (int k = 0; k < 2; ++k) dst[n][k] = *(const PG8_LAS bf16x8*)(lds + PG8_SB(b, h) + boff + n * 2048 + k * 1024); } while (0)
; #define PG8_MMA(ai, bj, At, Bt) do { __builtin_amdgcn_s_setprio(1); _Pragma("unroll") for (int m = 0; m < 4; ++m) _Pragma("unroll") for (int n = 0; n < 2; ++n) _Pragma("unroll") for (int k = 0; k < 2; ++k) \
;         acc[ai][bj][m][n] = __builtin_amdgcn_mfma_f32_16x16x32_bf16(Bt[n][k], At[m][k], acc[ai][bj][m][n], 0, 0, 0); __builtin_amdgcn_s_setprio(0); } while (0)
; #define PG8_WAIT_V(n) asm volatile("s_waitcnt vmcnt(" #n ")" ::: "memory")
; #define PG8_WAIT_L(n) asm volatile("s_waitcnt lgkmcnt(" #n ")" ::: "memory")
; #define PG8_BAR __builtin_amdgcn_s_barrier()
; #define PG8_SCHED __builtin_amdgcn_sched_barrier(0)
; template <class Epi, class Sched, bool ALIGN_EPI = false, bool SP2 = false>
; __device__ __forceinline__ void gemm_phase(PG8_LAS unsigned char* lds, const Gemm g, const Sched& S, const Epi& E) {
;     ...
;             PG8_WAIT_V(8); PG8_WAIT_L(0); PG8_BAR; PG8_MMA(1, 0, At, B0); PG8_MMA(1, 1, At, B1); PG8_BAR; PG8_SCHED;
;             PG8_LDB(B0, 1, 0); PG8_LDB(B1, 1, 1); PG8_SCHED; PG8_LDA(At, 1, 0); PG8_STAGE(PG8_SA(0, 1), a2 + hstep, voffA);
;             PG8_WAIT_V(8); PG8_WAIT_L(0); PG8_BAR; PG8_MMA(0, 0, At, B0); PG8_MMA(0, 1, At, B1); PG8_BAR; PG8_SCHED;
	s_setprio 1
	s_waitcnt lgkmcnt(0)
	v_mfma_f32_16x16x32_bf16 v[62:65], v[144:147], v[188:191], v[62:65]
	v_mfma_f32_16x16x32_bf16 v[62:65], v[160:163], v[206:209], v[62:65]
	v_mfma_f32_16x16x32_bf16 v[58:61], v[168:171], v[206:209], v[58:61]
	v_mfma_f32_16x16x32_bf16 v[58:61], v[164:167], v[188:191], v[58:61]
	v_mfma_f32_16x16x32_bf16 v[42:45], v[164:167], v[210:213], v[42:45]
	v_mfma_f32_16x16x32_bf16 v[42:45], v[168:171], v[214:217], v[42:45]
	v_mfma_f32_16x16x32_bf16 v[46:49], v[160:163], v[214:217], v[46:49]
	v_mfma_f32_16x16x32_bf16 v[46:49], v[144:147], v[210:213], v[46:49]
	v_mfma_f32_16x16x32_bf16 v[30:33], v[144:147], v[218:221], v[30:33]
	v_mfma_f32_16x16x32_bf16 v[30:33], v[160:163], v[222:225], v[30:33]
	v_mfma_f32_16x16x32_bf16 v[26:29], v[168:171], v[222:225], v[26:29]
	v_mfma_f32_16x16x32_bf16 v[26:29], v[164:167], v[218:221], v[26:29]
	v_mfma_f32_16x16x32_bf16 v[10:13], v[164:167], v[226:229], v[10:13]
	v_mfma_f32_16x16x32_bf16 v[10:13], v[168:171], v[230:233], v[10:13]
	v_mfma_f32_16x16x32_bf16 v[14:17], v[160:163], v[230:233], v[14:17]
	v_mfma_f32_16x16x32_bf16 v[14:17], v[144:147], v[226:229], v[14:17]
	s_setprio 0
	s_setprio 1
	v_mfma_f32_16x16x32_bf16 v[54:57], v[172:175], v[188:191], v[54:57]
	v_mfma_f32_16x16x32_bf16 v[54:57], v[176:179], v[206:209], v[54:57]
	v_mfma_f32_16x16x32_bf16 v[50:53], v[184:187], v[206:209], v[50:53]
	v_mfma_f32_16x16x32_bf16 v[50:53], v[180:183], v[188:191], v[50:53]
	v_mfma_f32_16x16x32_bf16 v[34:37], v[180:183], v[210:213], v[34:37]
	v_mfma_f32_16x16x32_bf16 v[34:37], v[184:187], v[214:217], v[34:37]
	v_mfma_f32_16x16x32_bf16 v[38:41], v[176:179], v[214:217], v[38:41]
	v_mfma_f32_16x16x32_bf16 v[38:41], v[172:175], v[210:213], v[38:41]
	v_mfma_f32_16x16x32_bf16 v[22:25], v[172:175], v[218:221], v[22:25]
	v_mfma_f32_16x16x32_bf16 v[22:25], v[176:179], v[222:225], v[22:25]
	v_mfma_f32_16x16x32_bf16 v[18:21], v[184:187], v[222:225], v[18:21]
	v_mfma_f32_16x16x32_bf16 v[18:21], v[180:183], v[218:221], v[18:21]
	v_mfma_f32_16x16x32_bf16 v[2:5], v[180:183], v[226:229], v[2:5]
	v_mfma_f32_16x16x32_bf16 v[2:5], v[184:187], v[230:233], v[2:5]
	v_mfma_f32_16x16x32_bf16 v[6:9], v[176:179], v[230:233], v[6:9]
	s_barrier
	v_mfma_f32_16x16x32_bf16 v[6:9], v[172:175], v[226:229], v[6:9]
	s_setprio 0
	s_add_i32 s72, 0, 0x18000
	v_add_u32_e32 v153, s72, v150
	s_add_i32 s73, 0, 0x1c000
	ds_read_b128 v[144:147], v153
	ds_read_b128 v[160:163], v153 offset:1024
	ds_read_b128 v[164:167], v153 offset:2048
	ds_read_b128 v[168:171], v153 offset:3072
	v_add_u32_e32 v153, s73, v150
	ds_read_b128 v[172:175], v153
	ds_read_b128 v[176:179], v153 offset:1024
	ds_read_b128 v[180:183], v153 offset:2048
	ds_read_b128 v[184:187], v153 offset:3072
	s_add_u32 s24, s46, 0x40000
	s_addc_u32 s25, s47, 0
	s_mov_b32 m0, s57
	v_lshl_add_u64 v[236:237], s[24:25], 0, v[130:131]
	ds_read_b128 v[188:191], v152 offset:32768
	ds_read_b128 v[206:209], v152 offset:33792
	ds_read_b128 v[210:213], v152 offset:34816
	ds_read_b128 v[214:217], v152 offset:35840
	ds_read_b128 v[218:221], v152 offset:36864
	ds_read_b128 v[222:225], v152 offset:37888
	ds_read_b128 v[226:229], v152 offset:38912
	ds_read_b128 v[230:233], v152 offset:39936
	global_load_lds_dwordx4 v[236:237], off
	v_lshl_add_u64 v[236:237], s[24:25], 0, v[134:135]
	s_mov_b32 m0, s58
	s_nop 0
	global_load_lds_dwordx4 v[236:237], off
	s_waitcnt vmcnt(8)
	s_waitcnt lgkmcnt(0)
	s_barrier
	s_setprio 1
	s_waitcnt lgkmcnt(0)
	v_mfma_f32_16x16x32_bf16 v[126:129], v[144:147], v[188:191], v[126:129]
	v_mfma_f32_16x16x32_bf16 v[126:129], v[160:163], v[206:209], v[126:129]
	v_mfma_f32_16x16x32_bf16 v[122:125], v[168:171], v[206:209], v[122:125]
	v_mfma_f32_16x16x32_bf16 v[122:125], v[164:167], v[188:191], v[122:125]
	v_mfma_f32_16x16x32_bf16 v[106:109], v[164:167], v[210:213], v[106:109]
	v_mfma_f32_16x16x32_bf16 v[106:109], v[168:171], v[214:217], v[106:109]
	v_mfma_f32_16x16x32_bf16 v[110:113], v[160:163], v[214:217], v[110:113]
	v_mfma_f32_16x16x32_bf16 v[110:113], v[144:147], v[210:213], v[110:113]
	v_mfma_f32_16x16x32_bf16 v[94:97], v[144:147], v[218:221], v[94:97]
	v_mfma_f32_16x16x32_bf16 v[94:97], v[160:163], v[222:225], v[94:97]
	v_mfma_f32_16x16x32_bf16 v[90:93], v[168:171], v[222:225], v[90:93]
	v_mfma_f32_16x16x32_bf16 v[90:93], v[164:167], v[218:221], v[90:93]
	v_mfma_f32_16x16x32_bf16 v[74:77], v[164:167], v[226:229], v[74:77]
	v_mfma_f32_16x16x32_bf16 v[74:77], v[168:171], v[230:233], v[74:77]
	v_mfma_f32_16x16x32_bf16 v[78:81], v[160:163], v[230:233], v[78:81]
	v_mfma_f32_16x16x32_bf16 v[78:81], v[144:147], v[226:229], v[78:81]
	s_setprio 0
	s_setprio 1
	v_mfma_f32_16x16x32_bf16 v[118:121], v[172:175], v[188:191], v[118:121]
	v_mfma_f32_16x16x32_bf16 v[118:121], v[176:179], v[206:209], v[118:121]
	v_mfma_f32_16x16x32_bf16 v[114:117], v[184:187], v[206:209], v[114:117]
	v_mfma_f32_16x16x32_bf16 v[114:117], v[180:183], v[188:191], v[114:117]
	v_mfma_f32_16x16x32_bf16 v[98:101], v[180:183], v[210:213], v[98:101]
	v_mfma_f32_16x16x32_bf16 v[98:101], v[184:187], v[214:217], v[98:101]
	v_mfma_f32_16x16x32_bf16 v[102:105], v[176:179], v[214:217], v[102:105]
	v_mfma_f32_16x16x32_bf16 v[102:105], v[172:175], v[210:213], v[102:105]
	v_mfma_f32_16x16x32_bf16 v[86:89], v[172:175], v[218:221], v[86:89]
	v_mfma_f32_16x16x32_bf16 v[86:89], v[176:179], v[222:225], v[86:89]
	v_mfma_f32_16x16x32_bf16 v[82:85], v[184:187], v[222:225], v[82:85]
	v_mfma_f32_16x16x32_bf16 v[82:85], v[180:183], v[218:221], v[82:85]
	v_mfma_f32_16x16x32_bf16 v[66:69], v[180:183], v[226:229], v[66:69]
	v_mfma_f32_16x16x32_bf16 v[66:69], v[184:187], v[230:233], v[66:69]
	v_mfma_f32_16x16x32_bf16 v[70:73], v[176:179], v[230:233], v[70:73]
	s_barrier
; #define PG8_STAGE(bufoff, gbase, voff) do { _Pragma("unroll") for (int _i = 0; _i < 2; ++_i) \
;         __builtin_amdgcn_global_load_lds((const unsigned*)((const char*)(gbase) + (voff)[_i]), (PG8_LAS unsigned*)(lds + (bufoff) + ldsw + _i * 8192), 16, 0, 0); } while (0)
; #define PG8_LDA(dst, b, h) do { _Pragma("unroll") for (int m = 0; m < 4; ++m) _Pragma("unroll") for (int k = 0; k < 2; ++k) dst[m][k] = *(const PG8_LAS bf16x8*)(lds + PG8_SA(b, h) + aoff + m * 2048 + k * 1024); } while (0)
; #define PG8_MMA(ai, bj, At, Bt) do { __builtin_amdgcn_s_setprio(1); _Pragma("unroll") for (int m = 0; m < 4; ++m) _Pragma("unroll") for (int n = 0; n < 2; ++n) _Pragma("unroll") for (int k = 0; k < 2; ++k) \
;         acc[ai][bj][m][n] = __builtin_amdgcn_mfma_f32_16x16x32_bf16(Bt[n][k], At[m][k], acc[ai][bj][m][n], 0, 0, 0); __builtin_amdgcn_s_setprio(0); } while (0)
; #define PG8_WAIT_V(n) asm volatile("s_waitcnt vmcnt(" #n ")" ::: "memory")
; #define PG8_WAIT_L(n) asm volatile("s_waitcnt lgkmcnt(" #n ")" ::: "memory")
; #define PG8_BAR __builtin_amdgcn_s_barrier()
; #define PG8_SCHED __builtin_amdgcn_sched_barrier(0)
; template <class Epi, class Sched, bool ALIGN_EPI = false, bool SP2 = false>
; __device__ __forceinline__ void gemm_phase(PG8_LAS unsigned char* lds, const Gemm g, const Sched& S, const Epi& E) {
;     ...
;             PG8_WAIT_V(8); PG8_WAIT_L(0); PG8_BAR; PG8_MMA(0, 0, At, B0); PG8_MMA(0, 1, At, B1); PG8_BAR; PG8_SCHED;
;             PG8_LDA(At, 1, 1); PG8_STAGE(PG8_SB(1, 0), b3, voffB); PG8_STAGE(PG8_SB(1, 1), b3 + hstep, voffB); PG8_STAGE(PG8_SA(1, 0), a3, voffA);
;             PG8_WAIT_V(8); PG8_WAIT_L(0); PG8_BAR; PG8_MMA(1, 0, At, B0); PG8_MMA(1, 1, At, B1); PG8_BAR; PG8_SCHED;
	v_mfma_f32_16x16x32_bf16 v[70:73], v[172:175], v[226:229], v[70:73]
	s_setprio 0
	s_add_i32 s24, s72, s51
	v_lshl_add_u64 v[148:149], v[148:149], 0, s[38:39]
	s_mov_b32 m0, s24
	ds_read_b128 v[188:191], v152 offset:49152
	ds_read_b128 v[206:209], v152 offset:50176
	ds_read_b128 v[210:213], v152 offset:51200
	ds_read_b128 v[214:217], v152 offset:52224
	ds_read_b128 v[218:221], v152 offset:53248
	ds_read_b128 v[222:225], v152 offset:54272
	ds_read_b128 v[226:229], v152 offset:55296
	ds_read_b128 v[230:233], v152 offset:56320
	global_load_lds_dwordx4 v[148:149], off
	s_add_i32 m0, s24, 0x2000
	s_add_u32 s24, s42, 0x40080
	v_lshl_add_u64 v[148:149], v[234:235], 0, s[38:39]
	s_addc_u32 s25, s43, 0
	s_add_i32 s42, s73, s51
	global_load_lds_dwordx4 v[148:149], off
	v_lshl_add_u64 v[148:149], s[24:25], 0, v[132:133]
	s_mov_b32 m0, s42
	s_nop 0
	global_load_lds_dwordx4 v[148:149], off
	v_lshl_add_u64 v[148:149], s[24:25], 0, v[136:137]
	s_add_i32 m0, s42, 0x2000
	s_nop 0
	global_load_lds_dwordx4 v[148:149], off
	v_lshl_add_u64 v[148:149], s[26:27], 0, v[130:131]
	s_mov_b32 m0, s64
	s_nop 0
	global_load_lds_dwordx4 v[148:149], off
	v_lshl_add_u64 v[148:149], s[26:27], 0, v[134:135]
	s_mov_b32 m0, s65
	s_nop 0
	global_load_lds_dwordx4 v[148:149], off
	s_waitcnt vmcnt(8)
	s_waitcnt lgkmcnt(0)
	s_barrier
	s_setprio 1
	s_waitcnt lgkmcnt(0)
	v_mfma_f32_16x16x32_bf16 v[62:65], v[144:147], v[188:191], v[62:65]
	v_mfma_f32_16x16x32_bf16 v[62:65], v[160:163], v[206:209], v[62:65]
	v_mfma_f32_16x16x32_bf16 v[58:61], v[168:171], v[206:209], v[58:61]
	v_mfma_f32_16x16x32_bf16 v[58:61], v[164:167], v[188:191], v[58:61]
	v_mfma_f32_16x16x32_bf16 v[42:45], v[164:167], v[210:213], v[42:45]
	v_mfma_f32_16x16x32_bf16 v[42:45], v[168:171], v[214:217], v[42:45]
	v_mfma_f32_16x16x32_bf16 v[46:49], v[160:163], v[214:217], v[46:49]
	v_mfma_f32_16x16x32_bf16 v[46:49], v[144:147], v[210:213], v[46:49]
	v_mfma_f32_16x16x32_bf16 v[30:33], v[144:147], v[218:221], v[30:33]
	v_mfma_f32_16x16x32_bf16 v[30:33], v[160:163], v[222:225], v[30:33]
	v_mfma_f32_16x16x32_bf16 v[26:29], v[168:171], v[222:225], v[26:29]
	v_mfma_f32_16x16x32_bf16 v[26:29], v[164:167], v[218:221], v[26:29]
	v_mfma_f32_16x16x32_bf16 v[10:13], v[164:167], v[226:229], v[10:13]
	v_mfma_f32_16x16x32_bf16 v[10:13], v[168:171], v[230:233], v[10:13]
	v_mfma_f32_16x16x32_bf16 v[14:17], v[160:163], v[230:233], v[14:17]
	v_mfma_f32_16x16x32_bf16 v[14:17], v[144:147], v[226:229], v[14:17]
	s_setprio 0
	s_setprio 1
	v_mfma_f32_16x16x32_bf16 v[54:57], v[172:175], v[188:191], v[54:57]
	v_mfma_f32_16x16x32_bf16 v[54:57], v[176:179], v[206:209], v[54:57]
	v_mfma_f32_16x16x32_bf16 v[50:53], v[184:187], v[206:209], v[50:53]
	v_mfma_f32_16x16x32_bf16 v[50:53], v[180:183], v[188:191], v[50:53]
	v_mfma_f32_16x16x32_bf16 v[34:37], v[180:183], v[210:213], v[34:37]
	v_mfma_f32_16x16x32_bf16 v[34:37], v[184:187], v[214:217], v[34:37]
	v_mfma_f32_16x16x32_bf16 v[38:41], v[176:179], v[214:217], v[38:41]
	v_mfma_f32_16x16x32_bf16 v[38:41], v[172:175], v[210:213], v[38:41]
	v_mfma_f32_16x16x32_bf16 v[22:25], v[172:175], v[218:221], v[22:25]
	v_mfma_f32_16x16x32_bf16 v[22:25], v[176:179], v[222:225], v[22:25]
	v_mfma_f32_16x16x32_bf16 v[18:21], v[184:187], v[222:225], v[18:21]
	v_mfma_f32_16x16x32_bf16 v[18:21], v[180:183], v[218:221], v[18:21]
	v_mfma_f32_16x16x32_bf16 v[2:5], v[180:183], v[226:229], v[2:5]
	v_mfma_f32_16x16x32_bf16 v[2:5], v[184:187], v[230:233], v[2:5]
	v_mfma_f32_16x16x32_bf16 v[6:9], v[176:179], v[230:233], v[6:9]
	s_barrier
	v_mfma_f32_16x16x32_bf16 v[6:9], v[172:175], v[226:229], v[6:9]
	s_setprio 0
	s_add_i32 s71, s71, 2
	s_add_u32 s69, s69, 0x100
	s_addc_u32 s70, s70, 0
	s_cmp_gt_u32 s71, 13
	s_mov_b64 s[24:25], s[2:3]
	s_cbranch_scc0 .LBB0_238
	s_and_b64 vcc, exec, s[6:7]
	s_cbranch_vccz .LBB0_241
	s_barrier

; #define PG8_STAGE(bufoff, gbase, voff) do { _Pragma("unroll") for (int _i = 0; _i < 2; ++_i) \
;         __builtin_amdgcn_global_load_lds((const unsigned*)((const char*)(gbase) + (voff)[_i]), (PG8_LAS unsigned*)(lds + (bufoff) + ldsw + _i * 8192), 16, 0, 0); } while (0)
; #define PG8_LDA(dst, b, h) do { _Pragma("unroll") for (int m = 0; m < 4; ++m) _Pragma("unroll") for (int k = 0; k < 2; ++k) dst[m][k] = *(const PG8_LAS bf16x8*)(lds + PG8_SA(b, h) + aoff + m * 2048 + k * 1024); } while (0)
; #define PG8_LDB(dst, b, h) do { _Pragma("unroll") for (int n = 0; n < 2; ++n) _Pragma("unroll") for (int k = 0; k < 2; ++k) dst[n][k] = *(const PG8_LAS bf16x8*)(lds + PG8_SB(b, h) + boff + n * 2048 + k * 1024); } while (0)
; #define PG8_MMA(ai, bj, At, Bt) do { __builtin_amdgcn_s_setprio(1); _Pragma("unroll") for (int m = 0; m < 4; ++m) _Pragma("unroll") for (int n = 0; n < 2; ++n) _Pragma("unroll") for (int k = 0; k < 2; ++k) \
;         acc[ai][bj][m][n] = __builtin_amdgcn_mfma_f32_16x16x32_bf16(Bt[n][k], At[m][k], acc[ai][bj][m][n], 0, 0, 0); __builtin_amdgcn_s_setprio(0); } while (0)
; #define PG8_WAIT_V(n) asm volatile("s_waitcnt vmcnt(" #n ")" ::: "memory")
; #define PG8_BAR __builtin_amdgcn_s_barrier()
; template <class Epi, class Sched, bool ALIGN_EPI = false, bool SP2 = false>
; __device__ __forceinline__ void gemm_phase(PG8_LAS unsigned char* lds, const Gemm g, const Sched& S, const Epi& E) {
;     ...
;         for (int t = 0; t < nt; t += 2) {
;             const bool last = (t == nt - 2);
;             const char* a1 = cA + (size_t)(t + 1) * kstepA;
;             const char* a2 = last ? nA : cA + (size_t)(t + 2) * kstepA; const char* b2 = last ? nB : cB + (size_t)(t + 2) * kstep;
;             const char* a3 = a2 + kstepA; const char* b3 = b2 + kstep;
;             if (last && has_next) S.a_ready(nxt);
;             if constexpr (SP2) {
;             PG8_LDB(B0, 0, 0); PG8_LDB(B1, 0, 1); PG8_SCHED; PG8_LDA(At, 0, 0); PG8_STAGE(PG8_SA(1, 1), a1 + hstep, voffA);
;             PG8_WAIT_V(8); PG8_WAIT_L(0); PG8_BAR; PG8_MMA(0, 0, At, B0); PG8_MMA(0, 1, At, B1); PG8_BAR; PG8_SCHED;
;             PG8_LDA(At, 0, 1); PG8_STAGE(PG8_SB(0, 0), b2, voffB); PG8_STAGE(PG8_SB(0, 1), b2 + hstep, voffB); PG8_STAGE(PG8_SA(0, 0), a2, voffA);
;             PG8_WAIT_V(8); PG8_WAIT_L(0); PG8_BAR; PG8_MMA(1, 0, At, B0); PG8_MMA(1, 1, At, B1); PG8_BAR; PG8_SCHED;
.LBB0_310:
	s_add_i32 s49, s24, 2
	s_add_u32 s25, s2, 0x4000
	s_addc_u32 s26, s3, 0
	s_cmp_eq_u32 s59, s24
	s_cselect_b32 s27, s9, s26
	s_cselect_b32 s26, s8, s25
	s_cselect_b32 s66, s44, s47
	s_cselect_b32 s67, s45, s48
	s_add_u32 s24, s26, 0x4000
	s_addc_u32 s25, s27, 0
	s_add_i32 s65, 0, 0x14000
	v_add_u32_e32 v142, s76, v187
	v_add_u32_e32 v167, s65, v187
	ds_read_b128 v[130:133], v142
	ds_read_b128 v[134:137], v142 offset:1024
	ds_read_b128 v[138:141], v142 offset:2048
	ds_read_b128 v[142:145], v142 offset:3072
	ds_read_b128 v[146:149], v167
	ds_read_b128 v[150:153], v167 offset:1024
	ds_read_b128 v[206:209], v167 offset:2048
	ds_read_b128 v[210:213], v167 offset:3072
	v_lshl_add_u64 v[184:185], s[2:3], 0, v[182:183]
	s_add_i32 m0, s51, 0xc000
	ds_read_b128 v[214:217], v188
	ds_read_b128 v[218:221], v188 offset:1024
	ds_read_b128 v[222:225], v188 offset:2048
	ds_read_b128 v[226:229], v188 offset:3072
	ds_read_b128 v[230:233], v188 offset:4096
	ds_read_b128 v[234:237], v188 offset:5120
	ds_read_b128 v[238:241], v188 offset:6144
	ds_read_b128 v[242:245], v188 offset:7168
	global_load_lds_dwordx4 v[184:185], off
	v_lshl_add_u64 v[184:185], s[2:3], 0, v[180:181]
	s_add_i32 m0, s51, 0xe000
	s_nop 0
	global_load_lds_dwordx4 v[184:185], off
	s_waitcnt vmcnt(8)
	s_waitcnt lgkmcnt(0)
	s_barrier
	s_setprio 1
	s_waitcnt lgkmcnt(0)
	v_mfma_f32_16x16x32_bf16 v[126:129], v[130:133], v[214:217], v[126:129]
	v_mfma_f32_16x16x32_bf16 v[126:129], v[134:137], v[218:221], v[126:129]
	v_mfma_f32_16x16x32_bf16 v[122:125], v[142:145], v[218:221], v[122:125]
	v_mfma_f32_16x16x32_bf16 v[122:125], v[138:141], v[214:217], v[122:125]
	v_mfma_f32_16x16x32_bf16 v[106:109], v[138:141], v[222:225], v[106:109]
	v_mfma_f32_16x16x32_bf16 v[106:109], v[142:145], v[226:229], v[106:109]
	v_mfma_f32_16x16x32_bf16 v[110:113], v[134:137], v[226:229], v[110:113]
	v_mfma_f32_16x16x32_bf16 v[110:113], v[130:133], v[222:225], v[110:113]
	v_mfma_f32_16x16x32_bf16 v[94:97], v[130:133], v[230:233], v[94:97]
	v_mfma_f32_16x16x32_bf16 v[94:97], v[134:137], v[234:237], v[94:97]
	v_mfma_f32_16x16x32_bf16 v[90:93], v[142:145], v[234:237], v[90:93]
	v_mfma_f32_16x16x32_bf16 v[90:93], v[138:141], v[230:233], v[90:93]
	v_mfma_f32_16x16x32_bf16 v[74:77], v[138:141], v[238:241], v[74:77]
	v_mfma_f32_16x16x32_bf16 v[74:77], v[142:145], v[242:245], v[74:77]
	v_mfma_f32_16x16x32_bf16 v[78:81], v[134:137], v[242:245], v[78:81]
	v_mfma_f32_16x16x32_bf16 v[78:81], v[130:133], v[238:241], v[78:81]
	s_setprio 0
	s_setprio 1
	v_mfma_f32_16x16x32_bf16 v[118:121], v[146:149], v[214:217], v[118:121]
	v_mfma_f32_16x16x32_bf16 v[118:121], v[150:153], v[218:221], v[118:121]
	v_mfma_f32_16x16x32_bf16 v[114:117], v[210:213], v[218:221], v[114:117]
	v_mfma_f32_16x16x32_bf16 v[114:117], v[206:209], v[214:217], v[114:117]
	v_mfma_f32_16x16x32_bf16 v[98:101], v[206:209], v[222:225], v[98:101]
	v_mfma_f32_16x16x32_bf16 v[98:101], v[210:213], v[226:229], v[98:101]
	v_mfma_f32_16x16x32_bf16 v[102:105], v[150:153], v[226:229], v[102:105]
	v_mfma_f32_16x16x32_bf16 v[102:105], v[146:149], v[222:225], v[102:105]
	v_mfma_f32_16x16x32_bf16 v[86:89], v[146:149], v[230:233], v[86:89]
	v_mfma_f32_16x16x32_bf16 v[86:89], v[150:153], v[234:237], v[86:89]
	v_mfma_f32_16x16x32_bf16 v[82:85], v[210:213], v[234:237], v[82:85]
	v_mfma_f32_16x16x32_bf16 v[82:85], v[206:209], v[230:233], v[82:85]
	v_mfma_f32_16x16x32_bf16 v[66:69], v[206:209], v[238:241], v[66:69]
	v_mfma_f32_16x16x32_bf16 v[66:69], v[210:213], v[242:245], v[66:69]
	v_mfma_f32_16x16x32_bf16 v[70:73], v[150:153], v[242:245], v[70:73]
	s_barrier
	v_mfma_f32_16x16x32_bf16 v[70:73], v[146:149], v[238:241], v[70:73]
	s_setprio 0
	s_add_i32 s68, s76, s50
	v_lshl_add_u64 v[184:185], s[66:67], 0, v[0:1]
	s_mov_b32 m0, s68
	ds_read_b128 v[214:217], v188 offset:16384
	ds_read_b128 v[218:221], v188 offset:17408
	ds_read_b128 v[222:225], v188 offset:18432
	ds_read_b128 v[226:229], v188 offset:19456
	ds_read_b128 v[230:233], v188 offset:20480
	ds_read_b128 v[234:237], v188 offset:21504
	ds_read_b128 v[238:241], v188 offset:22528
	ds_read_b128 v[242:245], v188 offset:23552
	global_load_lds_dwordx4 v[184:185], off
	s_add_i32 m0, s68, 0x2000
	v_lshl_add_u64 v[190:191], s[66:67], 0, v[164:165]
	s_add_u32 s66, s66, s12
	s_addc_u32 s67, s67, 0
	s_add_i32 s65, s65, s50
	global_load_lds_dwordx4 v[190:191], off
	v_lshl_add_u64 v[246:247], s[66:67], 0, v[0:1]
	s_mov_b32 m0, s65
	v_lshl_add_u64 v[248:249], s[66:67], 0, v[164:165]
	global_load_lds_dwordx4 v[246:247], off
	s_add_i32 m0, s65, 0x2000
	v_lshl_add_u64 v[250:251], s[26:27], 0, v[160:161]
	global_load_lds_dwordx4 v[248:249], off
	s_mov_b32 m0, s51
	s_nop 0
	global_load_lds_dwordx4 v[250:251], off
	v_lshl_add_u64 v[250:251], s[26:27], 0, v[162:163]
	s_mov_b32 m0, s52
	s_nop 0
	global_load_lds_dwordx4 v[250:251], off
	s_waitcnt vmcnt(8)
	s_waitcnt lgkmcnt(0)
	s_barrier
; #define PG8_STAGE(bufoff, gbase, voff) do { _Pragma("unroll") for (int _i = 0; _i < 2; ++_i) \
;         __builtin_amdgcn_global_load_lds((const unsigned*)((const char*)(gbase) + (voff)[_i]), (PG8_LAS unsigned*)(lds + (bufoff) + ldsw + _i * 8192), 16, 0, 0); } while (0)
; #define PG8_LDA(dst, b, h) do { _Pragma("unroll") for (int m = 0; m < 4; ++m) _Pragma("unroll") for (int k = 0; k < 2; ++k) dst[m][k] = *(const PG8_LAS bf16x8*)(lds + PG8_SA(b, h) + aoff + m * 2048 + k * 1024); } while (0)
; #define PG8_LDB(dst, b, h) do { _Pragma("unroll") for (int n = 0; n < 2; ++n) _Pragma("unroll") for (int k = 0; k < 2; ++k) dst[n][k] = *(const PG8_LAS bf16x8*)(lds + PG8_SB(b, h) + boff + n * 2048 + k * 1024); } while (0)
; #define PG8_MMA(ai, bj, At, Bt) do { __builtin_amdgcn_s_setprio(1); _Pragma("unroll") for (int m = 0; m < 4; ++m) _Pragma("unroll") for (int n = 0; n < 2; ++n) _Pragma("unroll") for (int k = 0; k < 2; ++k) \
;         acc[ai][bj][m][n] = __builtin_amdgcn_mfma_f32_16x16x32_bf16(Bt[n][k], At[m][k], acc[ai][bj][m][n], 0, 0, 0); __builtin_amdgcn_s_setprio(0); } while (0)
; #define PG8_WAIT_V(n) asm volatile("s_waitcnt vmcnt(" #n ")" ::: "memory")
; #define PG8_WAIT_L(n) asm volatile("s_waitcnt lgkmcnt(" #n ")" ::: "memory")
; #define PG8_BAR __builtin_amdgcn_s_barrier()
; #define PG8_SCHED __builtin_amdgcn_sched_barrier(0)
; template <class Epi, class Sched, bool ALIGN_EPI = false, bool SP2 = false>
; __device__ __forceinline__ void gemm_phase(PG8_LAS unsigned char* lds, const Gemm g, const Sched& S, const Epi& E) {
;     ...
;             PG8_WAIT_V(8); PG8_WAIT_L(0); PG8_BAR; PG8_MMA(1, 0, At, B0); PG8_MMA(1, 1, At, B1); PG8_BAR; PG8_SCHED;
;             PG8_LDB(B0, 1, 0); PG8_LDB(B1, 1, 1); PG8_SCHED; PG8_LDA(At, 1, 0); PG8_STAGE(PG8_SA(0, 1), a2 + hstep, voffA);
;             PG8_WAIT_V(8); PG8_WAIT_L(0); PG8_BAR; PG8_MMA(0, 0, At, B0); PG8_MMA(0, 1, At, B1); PG8_BAR; PG8_SCHED;
	s_setprio 1
	s_waitcnt lgkmcnt(0)
	v_mfma_f32_16x16x32_bf16 v[62:65], v[130:133], v[214:217], v[62:65]
	v_mfma_f32_16x16x32_bf16 v[62:65], v[134:137], v[218:221], v[62:65]
	v_mfma_f32_16x16x32_bf16 v[58:61], v[142:145], v[218:221], v[58:61]
	v_mfma_f32_16x16x32_bf16 v[58:61], v[138:141], v[214:217], v[58:61]
	v_mfma_f32_16x16x32_bf16 v[42:45], v[138:141], v[222:225], v[42:45]
	v_mfma_f32_16x16x32_bf16 v[42:45], v[142:145], v[226:229], v[42:45]
	v_mfma_f32_16x16x32_bf16 v[46:49], v[134:137], v[226:229], v[46:49]
	v_mfma_f32_16x16x32_bf16 v[46:49], v[130:133], v[222:225], v[46:49]
	v_mfma_f32_16x16x32_bf16 v[30:33], v[130:133], v[230:233], v[30:33]
	v_mfma_f32_16x16x32_bf16 v[30:33], v[134:137], v[234:237], v[30:33]
	v_mfma_f32_16x16x32_bf16 v[26:29], v[142:145], v[234:237], v[26:29]
	v_mfma_f32_16x16x32_bf16 v[26:29], v[138:141], v[230:233], v[26:29]
	v_mfma_f32_16x16x32_bf16 v[10:13], v[138:141], v[238:241], v[10:13]
	v_mfma_f32_16x16x32_bf16 v[10:13], v[142:145], v[242:245], v[10:13]
	v_mfma_f32_16x16x32_bf16 v[14:17], v[134:137], v[242:245], v[14:17]
	v_mfma_f32_16x16x32_bf16 v[14:17], v[130:133], v[238:241], v[14:17]
	s_setprio 0
	s_setprio 1
	v_mfma_f32_16x16x32_bf16 v[54:57], v[146:149], v[214:217], v[54:57]
	v_mfma_f32_16x16x32_bf16 v[54:57], v[150:153], v[218:221], v[54:57]
	v_mfma_f32_16x16x32_bf16 v[50:53], v[210:213], v[218:221], v[50:53]
	v_mfma_f32_16x16x32_bf16 v[50:53], v[206:209], v[214:217], v[50:53]
	v_mfma_f32_16x16x32_bf16 v[34:37], v[206:209], v[222:225], v[34:37]
	v_mfma_f32_16x16x32_bf16 v[34:37], v[210:213], v[226:229], v[34:37]
	v_mfma_f32_16x16x32_bf16 v[38:41], v[150:153], v[226:229], v[38:41]
	v_mfma_f32_16x16x32_bf16 v[38:41], v[146:149], v[222:225], v[38:41]
	v_mfma_f32_16x16x32_bf16 v[22:25], v[146:149], v[230:233], v[22:25]
	v_mfma_f32_16x16x32_bf16 v[22:25], v[150:153], v[234:237], v[22:25]
	v_mfma_f32_16x16x32_bf16 v[18:21], v[210:213], v[234:237], v[18:21]
	v_mfma_f32_16x16x32_bf16 v[18:21], v[206:209], v[230:233], v[18:21]
	v_mfma_f32_16x16x32_bf16 v[2:5], v[206:209], v[238:241], v[2:5]
	v_mfma_f32_16x16x32_bf16 v[2:5], v[210:213], v[242:245], v[2:5]
	v_mfma_f32_16x16x32_bf16 v[6:9], v[150:153], v[242:245], v[6:9]
	s_barrier
	v_mfma_f32_16x16x32_bf16 v[6:9], v[146:149], v[238:241], v[6:9]
	s_setprio 0
	s_add_i32 s65, 0, 0x18000
	s_add_i32 s66, 0, 0x1c000
	v_add_u32_e32 v142, s65, v187
	v_add_u32_e32 v167, s66, v187
	ds_read_b128 v[130:133], v142
	ds_read_b128 v[134:137], v142 offset:1024
	ds_read_b128 v[138:141], v142 offset:2048
	ds_read_b128 v[142:145], v142 offset:3072
	ds_read_b128 v[146:149], v167
	ds_read_b128 v[150:153], v167 offset:1024
	ds_read_b128 v[206:209], v167 offset:2048
	ds_read_b128 v[210:213], v167 offset:3072
	s_add_u32 s26, s26, s12
	s_addc_u32 s27, s27, 0
	s_mov_b32 m0, s53
	v_lshl_add_u64 v[250:251], s[26:27], 0, v[160:161]
	ds_read_b128 v[214:217], v188 offset:32768
	ds_read_b128 v[218:221], v188 offset:33792
	ds_read_b128 v[222:225], v188 offset:34816
	ds_read_b128 v[226:229], v188 offset:35840
	ds_read_b128 v[230:233], v188 offset:36864
	ds_read_b128 v[234:237], v188 offset:37888
	ds_read_b128 v[238:241], v188 offset:38912
	ds_read_b128 v[242:245], v188 offset:39936
	global_load_lds_dwordx4 v[250:251], off
	v_lshl_add_u64 v[250:251], s[26:27], 0, v[162:163]
	s_mov_b32 m0, s54
	s_nop 0
	global_load_lds_dwordx4 v[250:251], off
	s_waitcnt vmcnt(8)
	s_waitcnt lgkmcnt(0)
	s_barrier
	s_setprio 1
	s_waitcnt lgkmcnt(0)
	v_mfma_f32_16x16x32_bf16 v[126:129], v[130:133], v[214:217], v[126:129]
	v_mfma_f32_16x16x32_bf16 v[126:129], v[134:137], v[218:221], v[126:129]
	v_mfma_f32_16x16x32_bf16 v[122:125], v[142:145], v[218:221], v[122:125]
	v_mfma_f32_16x16x32_bf16 v[122:125], v[138:141], v[214:217], v[122:125]
	v_mfma_f32_16x16x32_bf16 v[106:109], v[138:141], v[222:225], v[106:109]
	v_mfma_f32_16x16x32_bf16 v[106:109], v[142:145], v[226:229], v[106:109]
	v_mfma_f32_16x16x32_bf16 v[110:113], v[134:137], v[226:229], v[110:113]
	v_mfma_f32_16x16x32_bf16 v[110:113], v[130:133], v[222:225], v[110:113]
	v_mfma_f32_16x16x32_bf16 v[94:97], v[130:133], v[230:233], v[94:97]
	v_mfma_f32_16x16x32_bf16 v[94:97], v[134:137], v[234:237], v[94:97]
	v_mfma_f32_16x16x32_bf16 v[90:93], v[142:145], v[234:237], v[90:93]
	v_mfma_f32_16x16x32_bf16 v[90:93], v[138:141], v[230:233], v[90:93]
	v_mfma_f32_16x16x32_bf16 v[74:77], v[138:141], v[238:241], v[74:77]
	v_mfma_f32_16x16x32_bf16 v[74:77], v[142:145], v[242:245], v[74:77]
	v_mfma_f32_16x16x32_bf16 v[78:81], v[134:137], v[242:245], v[78:81]
	v_mfma_f32_16x16x32_bf16 v[78:81], v[130:133], v[238:241], v[78:81]
	s_setprio 0
	s_setprio 1
	v_mfma_f32_16x16x32_bf16 v[118:121], v[146:149], v[214:217], v[118:121]
	v_mfma_f32_16x16x32_bf16 v[118:121], v[150:153], v[218:221], v[118:121]
	v_mfma_f32_16x16x32_bf16 v[114:117], v[210:213], v[218:221], v[114:117]
	v_mfma_f32_16x16x32_bf16 v[114:117], v[206:209], v[214:217], v[114:117]
	v_mfma_f32_16x16x32_bf16 v[98:101], v[206:209], v[222:225], v[98:101]
	v_mfma_f32_16x16x32_bf16 v[98:101], v[210:213], v[226:229], v[98:101]
	v_mfma_f32_16x16x32_bf16 v[102:105], v[150:153], v[226:229], v[102:105]
	v_mfma_f32_16x16x32_bf16 v[102:105], v[146:149], v[222:225], v[102:105]
	v_mfma_f32_16x16x32_bf16 v[86:89], v[146:149], v[230:233], v[86:89]
	v_mfma_f32_16x16x32_bf16 v[86:89], v[150:153], v[234:237], v[86:89]
	v_mfma_f32_16x16x32_bf16 v[82:85], v[210:213], v[234:237], v[82:85]
	v_mfma_f32_16x16x32_bf16 v[82:85], v[206:209], v[230:233], v[82:85]
	v_mfma_f32_16x16x32_bf16 v[66:69], v[206:209], v[238:241], v[66:69]
	v_mfma_f32_16x16x32_bf16 v[66:69], v[210:213], v[242:245], v[66:69]
	v_mfma_f32_16x16x32_bf16 v[70:73], v[150:153], v[242:245], v[70:73]
	s_barrier
; #define PG8_STAGE(bufoff, gbase, voff) do { _Pragma("unroll") for (int _i = 0; _i < 2; ++_i) \
;         __builtin_amdgcn_global_load_lds((const unsigned*)((const char*)(gbase) + (voff)[_i]), (PG8_LAS unsigned*)(lds + (bufoff) + ldsw + _i * 8192), 16, 0, 0); } while (0)
; #define PG8_LDA(dst, b, h) do { _Pragma("unroll") for (int m = 0; m < 4; ++m) _Pragma("unroll") for (int k = 0; k < 2; ++k) dst[m][k] = *(const PG8_LAS bf16x8*)(lds + PG8_SA(b, h) + aoff + m * 2048 + k * 1024); } while (0)
; #define PG8_MMA(ai, bj, At, Bt) do { __builtin_amdgcn_s_setprio(1); _Pragma("unroll") for (int m = 0; m < 4; ++m) _Pragma("unroll") for (int n = 0; n < 2; ++n) _Pragma("unroll") for (int k = 0; k < 2; ++k) \
;         acc[ai][bj][m][n] = __builtin_amdgcn_mfma_f32_16x16x32_bf16(Bt[n][k], At[m][k], acc[ai][bj][m][n], 0, 0, 0); __builtin_amdgcn_s_setprio(0); } while (0)
; #define PG8_WAIT_V(n) asm volatile("s_waitcnt vmcnt(" #n ")" ::: "memory")
; #define PG8_WAIT_L(n) asm volatile("s_waitcnt lgkmcnt(" #n ")" ::: "memory")
; #define PG8_BAR __builtin_amdgcn_s_barrier()
; #define PG8_SCHED __builtin_amdgcn_sched_barrier(0)
; template <class Epi, class Sched, bool ALIGN_EPI = false, bool SP2 = false>
; __device__ __forceinline__ void gemm_phase(PG8_LAS unsigned char* lds, const Gemm g, const Sched& S, const Epi& E) {
;     ...
;             PG8_WAIT_V(8); PG8_WAIT_L(0); PG8_BAR; PG8_MMA(0, 0, At, B0); PG8_MMA(0, 1, At, B1); PG8_BAR; PG8_SCHED;
;             PG8_LDA(At, 1, 1); PG8_STAGE(PG8_SB(1, 0), b3, voffB); PG8_STAGE(PG8_SB(1, 1), b3 + hstep, voffB); PG8_STAGE(PG8_SA(1, 0), a3, voffA);
;             PG8_WAIT_V(8); PG8_WAIT_L(0); PG8_BAR; PG8_MMA(1, 0, At, B0); PG8_MMA(1, 1, At, B1); PG8_BAR; PG8_SCHED;
	v_mfma_f32_16x16x32_bf16 v[70:73], v[146:149], v[238:241], v[70:73]
	s_setprio 0
	s_add_i32 s26, s65, s50
	v_lshl_add_u64 v[184:185], v[184:185], 0, s[38:39]
	s_mov_b32 m0, s26
	ds_read_b128 v[214:217], v188 offset:49152
	ds_read_b128 v[218:221], v188 offset:50176
	ds_read_b128 v[222:225], v188 offset:51200
	ds_read_b128 v[226:229], v188 offset:52224
	ds_read_b128 v[230:233], v188 offset:53248
	ds_read_b128 v[234:237], v188 offset:54272
	ds_read_b128 v[238:241], v188 offset:55296
	ds_read_b128 v[242:245], v188 offset:56320
	global_load_lds_dwordx4 v[184:185], off
	v_lshl_add_u64 v[184:185], v[190:191], 0, s[38:39]
	s_add_i32 m0, s26, 0x2000
	s_add_i32 s26, s66, s50
	global_load_lds_dwordx4 v[184:185], off
	v_lshl_add_u64 v[184:185], v[246:247], 0, s[38:39]
	s_mov_b32 m0, s26
	s_nop 0
	global_load_lds_dwordx4 v[184:185], off
	v_lshl_add_u64 v[184:185], v[248:249], 0, s[38:39]
	s_add_i32 m0, s26, 0x2000
	s_nop 0
	global_load_lds_dwordx4 v[184:185], off
	v_lshl_add_u64 v[184:185], s[24:25], 0, v[160:161]
	s_mov_b32 m0, s56
	s_nop 0
	global_load_lds_dwordx4 v[184:185], off
	v_lshl_add_u64 v[184:185], s[24:25], 0, v[162:163]
	s_mov_b32 m0, s57
	s_nop 0
	global_load_lds_dwordx4 v[184:185], off
	s_waitcnt vmcnt(8)
	s_waitcnt lgkmcnt(0)
	s_barrier
	s_setprio 1
	s_waitcnt lgkmcnt(0)
	v_mfma_f32_16x16x32_bf16 v[62:65], v[130:133], v[214:217], v[62:65]
	v_mfma_f32_16x16x32_bf16 v[62:65], v[134:137], v[218:221], v[62:65]
	v_mfma_f32_16x16x32_bf16 v[58:61], v[142:145], v[218:221], v[58:61]
	v_mfma_f32_16x16x32_bf16 v[58:61], v[138:141], v[214:217], v[58:61]
	v_mfma_f32_16x16x32_bf16 v[42:45], v[138:141], v[222:225], v[42:45]
	v_mfma_f32_16x16x32_bf16 v[42:45], v[142:145], v[226:229], v[42:45]
	v_mfma_f32_16x16x32_bf16 v[46:49], v[134:137], v[226:229], v[46:49]
	v_mfma_f32_16x16x32_bf16 v[46:49], v[130:133], v[222:225], v[46:49]
	v_mfma_f32_16x16x32_bf16 v[30:33], v[130:133], v[230:233], v[30:33]
	v_mfma_f32_16x16x32_bf16 v[30:33], v[134:137], v[234:237], v[30:33]
	v_mfma_f32_16x16x32_bf16 v[26:29], v[142:145], v[234:237], v[26:29]
	v_mfma_f32_16x16x32_bf16 v[26:29], v[138:141], v[230:233], v[26:29]
	v_mfma_f32_16x16x32_bf16 v[10:13], v[138:141], v[238:241], v[10:13]
	v_mfma_f32_16x16x32_bf16 v[10:13], v[142:145], v[242:245], v[10:13]
	v_mfma_f32_16x16x32_bf16 v[14:17], v[134:137], v[242:245], v[14:17]
	v_mfma_f32_16x16x32_bf16 v[14:17], v[130:133], v[238:241], v[14:17]
	s_setprio 0
	s_setprio 1
	v_mfma_f32_16x16x32_bf16 v[54:57], v[146:149], v[214:217], v[54:57]
	v_mfma_f32_16x16x32_bf16 v[54:57], v[150:153], v[218:221], v[54:57]
	v_mfma_f32_16x16x32_bf16 v[50:53], v[210:213], v[218:221], v[50:53]
	v_mfma_f32_16x16x32_bf16 v[50:53], v[206:209], v[214:217], v[50:53]
	v_mfma_f32_16x16x32_bf16 v[34:37], v[206:209], v[222:225], v[34:37]
	v_mfma_f32_16x16x32_bf16 v[34:37], v[210:213], v[226:229], v[34:37]
	v_mfma_f32_16x16x32_bf16 v[38:41], v[150:153], v[226:229], v[38:41]
	v_mfma_f32_16x16x32_bf16 v[38:41], v[146:149], v[222:225], v[38:41]
	v_mfma_f32_16x16x32_bf16 v[22:25], v[146:149], v[230:233], v[22:25]
	v_mfma_f32_16x16x32_bf16 v[22:25], v[150:153], v[234:237], v[22:25]
	v_mfma_f32_16x16x32_bf16 v[18:21], v[210:213], v[234:237], v[18:21]
	v_mfma_f32_16x16x32_bf16 v[18:21], v[206:209], v[230:233], v[18:21]
	v_mfma_f32_16x16x32_bf16 v[2:5], v[206:209], v[238:241], v[2:5]
	v_mfma_f32_16x16x32_bf16 v[2:5], v[210:213], v[242:245], v[2:5]
	v_mfma_f32_16x16x32_bf16 v[6:9], v[150:153], v[242:245], v[6:9]
	s_barrier
	v_mfma_f32_16x16x32_bf16 v[6:9], v[146:149], v[238:241], v[6:9]
	s_setprio 0
	s_add_u32 s47, s47, 0x100
	s_addc_u32 s48, s48, 0
	s_add_u32 s2, s2, 0x8000
	s_addc_u32 s3, s3, 0
	s_cmp_ge_u32 s49, s55
	s_mov_b32 s24, s49
	s_cbranch_scc0 .LBB0_310
	s_and_b64 vcc, exec, s[42:43]
	s_cbranch_vccz .LBB0_313
	s_barrier

; #define PG8_STAGE(bufoff, gbase, voff) do { _Pragma("unroll") for (int _i = 0; _i < 2; ++_i) \
;         __builtin_amdgcn_global_load_lds((const unsigned*)((const char*)(gbase) + (voff)[_i]), (PG8_LAS unsigned*)(lds + (bufoff) + ldsw + _i * 8192), 16, 0, 0); } while (0)
; #define PG8_LDA(dst, b, h) do { _Pragma("unroll") for (int m = 0; m < 4; ++m) _Pragma("unroll") for (int k = 0; k < 2; ++k) dst[m][k] = *(const PG8_LAS bf16x8*)(lds + PG8_SA(b, h) + aoff + m * 2048 + k * 1024); } while (0)
; #define PG8_LDB(dst, b, h) do { _Pragma("unroll") for (int n = 0; n < 2; ++n) _Pragma("unroll") for (int k = 0; k < 2; ++k) dst[n][k] = *(const PG8_LAS bf16x8*)(lds + PG8_SB(b, h) + boff + n * 2048 + k * 1024); } while (0)
; #define PG8_MMA(ai, bj, At, Bt) do { __builtin_amdgcn_s_setprio(1); _Pragma("unroll") for (int m = 0; m < 4; ++m) _Pragma("unroll") for (int n = 0; n < 2; ++n) _Pragma("unroll") for (int k = 0; k < 2; ++k) \
;         acc[ai][bj][m][n] = __builtin_amdgcn_mfma_f32_16x16x32_bf16(Bt[n][k], At[m][k], acc[ai][bj][m][n], 0, 0, 0); __builtin_amdgcn_s_setprio(0); } while (0)
; #define PG8_WAIT_V(n) asm volatile("s_waitcnt vmcnt(" #n ")" ::: "memory")
; #define PG8_BAR __builtin_amdgcn_s_barrier()
; template <class Epi, class Sched, bool ALIGN_EPI = false, bool SP2 = false>
; __device__ __forceinline__ void gemm_phase(PG8_LAS unsigned char* lds, const Gemm g, const Sched& S, const Epi& E) {
;     ...
;         for (int t = 0; t < nt; t += 2) {
;             const bool last = (t == nt - 2);
;             const char* a1 = cA + (size_t)(t + 1) * kstepA;
;             const char* a2 = last ? nA : cA + (size_t)(t + 2) * kstepA; const char* b2 = last ? nB : cB + (size_t)(t + 2) * kstep;
;             const char* a3 = a2 + kstepA; const char* b3 = b2 + kstep;
;             if (last && has_next) S.a_ready(nxt);
;             if constexpr (SP2) {
;             PG8_LDB(B0, 0, 0); PG8_LDB(B1, 0, 1); PG8_SCHED; PG8_LDA(At, 0, 0); PG8_STAGE(PG8_SA(1, 1), a1 + hstep, voffA);
;             PG8_WAIT_V(8); PG8_WAIT_L(0); PG8_BAR; PG8_MMA(0, 0, At, B0); PG8_MMA(0, 1, At, B1); PG8_BAR; PG8_SCHED;
;             PG8_LDA(At, 0, 1); PG8_STAGE(PG8_SB(0, 0), b2, voffB); PG8_STAGE(PG8_SB(0, 1), b2 + hstep, voffB); PG8_STAGE(PG8_SA(0, 0), a2, voffA);
;             PG8_WAIT_V(8); PG8_WAIT_L(0); PG8_BAR; PG8_MMA(1, 0, At, B0); PG8_MMA(1, 1, At, B1); PG8_BAR; PG8_SCHED;
.LBB0_409:
	s_add_u32 s24, s22, 0x8000
	s_addc_u32 s25, s23, 0
	s_cmp_eq_u32 s57, 12
	s_cselect_b32 s42, s53, s24
	s_cselect_b32 s43, s11, s25
	s_cselect_b32 s40, s54, s55
	s_cselect_b32 s41, s9, s56
	s_add_u32 s26, s42, 0x4000
	s_addc_u32 s27, s43, 0
	v_add_u32_e32 v145, s76, v142
	s_add_i32 s58, 0, 0x14000
	ds_read_b128 v[146:149], v145
	ds_read_b128 v[150:153], v145 offset:1024
	ds_read_b128 v[160:163], v145 offset:2048
	ds_read_b128 v[164:167], v145 offset:3072
	v_add_u32_e32 v145, s58, v142
	ds_read_b128 v[168:171], v145
	ds_read_b128 v[172:175], v145 offset:1024
	ds_read_b128 v[176:179], v145 offset:2048
	ds_read_b128 v[180:183], v145 offset:3072
	v_lshl_add_u64 v[230:231], s[22:23], 0, v[140:141]
	s_add_i32 m0, s45, 0xc000
	ds_read_b128 v[184:187], v144
	ds_read_b128 v[188:191], v144 offset:1024
	ds_read_b128 v[206:209], v144 offset:2048
	ds_read_b128 v[210:213], v144 offset:3072
	ds_read_b128 v[214:217], v144 offset:4096
	ds_read_b128 v[218:221], v144 offset:5120
	ds_read_b128 v[222:225], v144 offset:6144
	ds_read_b128 v[226:229], v144 offset:7168
	global_load_lds_dwordx4 v[230:231], off
	v_lshl_add_u64 v[230:231], s[22:23], 0, v[138:139]
	s_add_i32 m0, s45, 0xe000
	s_nop 0
	global_load_lds_dwordx4 v[230:231], off
	s_waitcnt vmcnt(8)
	s_waitcnt lgkmcnt(0)
	s_barrier
	s_setprio 1
	s_waitcnt lgkmcnt(0)
	v_mfma_f32_16x16x32_bf16 v[126:129], v[146:149], v[184:187], v[126:129]
	v_mfma_f32_16x16x32_bf16 v[126:129], v[150:153], v[188:191], v[126:129]
	v_mfma_f32_16x16x32_bf16 v[118:121], v[164:167], v[188:191], v[118:121]
	v_mfma_f32_16x16x32_bf16 v[118:121], v[160:163], v[184:187], v[118:121]
	v_mfma_f32_16x16x32_bf16 v[102:105], v[160:163], v[206:209], v[102:105]
	v_mfma_f32_16x16x32_bf16 v[102:105], v[164:167], v[210:213], v[102:105]
	v_mfma_f32_16x16x32_bf16 v[110:113], v[150:153], v[210:213], v[110:113]
	v_mfma_f32_16x16x32_bf16 v[110:113], v[146:149], v[206:209], v[110:113]
	v_mfma_f32_16x16x32_bf16 v[94:97], v[146:149], v[214:217], v[94:97]
	v_mfma_f32_16x16x32_bf16 v[94:97], v[150:153], v[218:221], v[94:97]
	v_mfma_f32_16x16x32_bf16 v[86:89], v[164:167], v[218:221], v[86:89]
	v_mfma_f32_16x16x32_bf16 v[86:89], v[160:163], v[214:217], v[86:89]
	v_mfma_f32_16x16x32_bf16 v[70:73], v[160:163], v[222:225], v[70:73]
	v_mfma_f32_16x16x32_bf16 v[70:73], v[164:167], v[226:229], v[70:73]
	v_mfma_f32_16x16x32_bf16 v[78:81], v[150:153], v[226:229], v[78:81]
	v_mfma_f32_16x16x32_bf16 v[78:81], v[146:149], v[222:225], v[78:81]
	s_setprio 0
	s_setprio 1
	v_mfma_f32_16x16x32_bf16 v[122:125], v[168:171], v[184:187], v[122:125]
	v_mfma_f32_16x16x32_bf16 v[122:125], v[172:175], v[188:191], v[122:125]
	v_mfma_f32_16x16x32_bf16 v[114:117], v[180:183], v[188:191], v[114:117]
	v_mfma_f32_16x16x32_bf16 v[114:117], v[176:179], v[184:187], v[114:117]
	v_mfma_f32_16x16x32_bf16 v[98:101], v[176:179], v[206:209], v[98:101]
	v_mfma_f32_16x16x32_bf16 v[98:101], v[180:183], v[210:213], v[98:101]
	v_mfma_f32_16x16x32_bf16 v[106:109], v[172:175], v[210:213], v[106:109]
	v_mfma_f32_16x16x32_bf16 v[106:109], v[168:171], v[206:209], v[106:109]
	v_mfma_f32_16x16x32_bf16 v[90:93], v[168:171], v[214:217], v[90:93]
	v_mfma_f32_16x16x32_bf16 v[90:93], v[172:175], v[218:221], v[90:93]
	v_mfma_f32_16x16x32_bf16 v[82:85], v[180:183], v[218:221], v[82:85]
	v_mfma_f32_16x16x32_bf16 v[82:85], v[176:179], v[214:217], v[82:85]
	v_mfma_f32_16x16x32_bf16 v[66:69], v[176:179], v[222:225], v[66:69]
	v_mfma_f32_16x16x32_bf16 v[66:69], v[180:183], v[226:229], v[66:69]
	v_mfma_f32_16x16x32_bf16 v[74:77], v[172:175], v[226:229], v[74:77]
	s_barrier
	v_mfma_f32_16x16x32_bf16 v[74:77], v[168:171], v[222:225], v[74:77]
	s_setprio 0
	s_add_i32 s22, s76, s29
	v_lshl_add_u64 v[230:231], s[40:41], 0, v[0:1]
	s_mov_b32 m0, s22
	ds_read_b128 v[184:187], v144 offset:16384
	ds_read_b128 v[188:191], v144 offset:17408
	ds_read_b128 v[206:209], v144 offset:18432
	ds_read_b128 v[210:213], v144 offset:19456
	ds_read_b128 v[214:217], v144 offset:20480
	ds_read_b128 v[218:221], v144 offset:21504
	ds_read_b128 v[222:225], v144 offset:22528
	ds_read_b128 v[226:229], v144 offset:23552
	global_load_lds_dwordx4 v[230:231], off
	s_add_i32 m0, s22, 0x2000
	s_add_u32 s22, s40, 0x40000
	v_lshl_add_u64 v[232:233], s[40:41], 0, v[130:131]
	s_addc_u32 s23, s41, 0
	s_add_i32 s58, s58, s29
	global_load_lds_dwordx4 v[232:233], off
	v_lshl_add_u64 v[234:235], s[22:23], 0, v[0:1]
	s_mov_b32 m0, s58
	s_nop 0
	global_load_lds_dwordx4 v[234:235], off
	v_lshl_add_u64 v[234:235], s[22:23], 0, v[130:131]
	s_add_i32 m0, s58, 0x2000
	s_nop 0
	global_load_lds_dwordx4 v[234:235], off
	v_lshl_add_u64 v[234:235], s[42:43], 0, v[134:135]
	s_mov_b32 m0, s45
	s_nop 0
	global_load_lds_dwordx4 v[234:235], off
	v_lshl_add_u64 v[234:235], s[42:43], 0, v[132:133]
	s_mov_b32 m0, s46
	s_nop 0
	global_load_lds_dwordx4 v[234:235], off
	s_waitcnt vmcnt(8)
	s_waitcnt lgkmcnt(0)
	s_barrier
; #define PG8_STAGE(bufoff, gbase, voff) do { _Pragma("unroll") for (int _i = 0; _i < 2; ++_i) \
;         __builtin_amdgcn_global_load_lds((const unsigned*)((const char*)(gbase) + (voff)[_i]), (PG8_LAS unsigned*)(lds + (bufoff) + ldsw + _i * 8192), 16, 0, 0); } while (0)
; #define PG8_LDA(dst, b, h) do { _Pragma("unroll") for (int m = 0; m < 4; ++m) _Pragma("unroll") for (int k = 0; k < 2; ++k) dst[m][k] = *(const PG8_LAS bf16x8*)(lds + PG8_SA(b, h) + aoff + m * 2048 + k * 1024); } while (0)
; #define PG8_LDB(dst, b, h) do { _Pragma("unroll") for (int n = 0; n < 2; ++n) _Pragma("unroll") for (int k = 0; k < 2; ++k) dst[n][k] = *(const PG8_LAS bf16x8*)(lds + PG8_SB(b, h) + boff + n * 2048 + k * 1024); } while (0)
; #define PG8_MMA(ai, bj, At, Bt) do { __builtin_amdgcn_s_setprio(1); _Pragma("unroll") for (int m = 0; m < 4; ++m) _Pragma("unroll") for (int n = 0; n < 2; ++n) _Pragma("unroll") for (int k = 0; k < 2; ++k) \
;         acc[ai][bj][m][n] = __builtin_amdgcn_mfma_f32_16x16x32_bf16(Bt[n][k], At[m][k], acc[ai][bj][m][n], 0, 0, 0); __builtin_amdgcn_s_setprio(0); } while (0)
; #define PG8_WAIT_V(n) asm volatile("s_waitcnt vmcnt(" #n ")" ::: "memory")
; #define PG8_WAIT_L(n) asm volatile("s_waitcnt lgkmcnt(" #n ")" ::: "memory")
; #define PG8_BAR __builtin_amdgcn_s_barrier()
; #define PG8_SCHED __builtin_amdgcn_sched_barrier(0)
; template <class Epi, class Sched, bool ALIGN_EPI = false, bool SP2 = false>
; __device__ __forceinline__ void gemm_phase(PG8_LAS unsigned char* lds, const Gemm g, const Sched& S, const Epi& E) {
;     ...
;             PG8_WAIT_V(8); PG8_WAIT_L(0); PG8_BAR; PG8_MMA(1, 0, At, B0); PG8_MMA(1, 1, At, B1); PG8_BAR; PG8_SCHED;
;             PG8_LDB(B0, 1, 0); PG8_LDB(B1, 1, 1); PG8_SCHED; PG8_LDA(At, 1, 0); PG8_STAGE(PG8_SA(0, 1), a2 + hstep, voffA);
;             PG8_WAIT_V(8); PG8_WAIT_L(0); PG8_BAR; PG8_MMA(0, 0, At, B0); PG8_MMA(0, 1, At, B1); PG8_BAR; PG8_SCHED;
	s_setprio 1
	s_waitcnt lgkmcnt(0)
	v_mfma_f32_16x16x32_bf16 v[62:65], v[146:149], v[184:187], v[62:65]
	v_mfma_f32_16x16x32_bf16 v[62:65], v[150:153], v[188:191], v[62:65]
	v_mfma_f32_16x16x32_bf16 v[54:57], v[164:167], v[188:191], v[54:57]
	v_mfma_f32_16x16x32_bf16 v[54:57], v[160:163], v[184:187], v[54:57]
	v_mfma_f32_16x16x32_bf16 v[38:41], v[160:163], v[206:209], v[38:41]
	v_mfma_f32_16x16x32_bf16 v[38:41], v[164:167], v[210:213], v[38:41]
	v_mfma_f32_16x16x32_bf16 v[46:49], v[150:153], v[210:213], v[46:49]
	v_mfma_f32_16x16x32_bf16 v[46:49], v[146:149], v[206:209], v[46:49]
	v_mfma_f32_16x16x32_bf16 v[30:33], v[146:149], v[214:217], v[30:33]
	v_mfma_f32_16x16x32_bf16 v[30:33], v[150:153], v[218:221], v[30:33]
	v_mfma_f32_16x16x32_bf16 v[22:25], v[164:167], v[218:221], v[22:25]
	v_mfma_f32_16x16x32_bf16 v[22:25], v[160:163], v[214:217], v[22:25]
	v_mfma_f32_16x16x32_bf16 v[6:9], v[160:163], v[222:225], v[6:9]
	v_mfma_f32_16x16x32_bf16 v[6:9], v[164:167], v[226:229], v[6:9]
	v_mfma_f32_16x16x32_bf16 v[14:17], v[150:153], v[226:229], v[14:17]
	v_mfma_f32_16x16x32_bf16 v[14:17], v[146:149], v[222:225], v[14:17]
	s_setprio 0
	s_setprio 1
	v_mfma_f32_16x16x32_bf16 v[58:61], v[168:171], v[184:187], v[58:61]
	v_mfma_f32_16x16x32_bf16 v[58:61], v[172:175], v[188:191], v[58:61]
	v_mfma_f32_16x16x32_bf16 v[50:53], v[180:183], v[188:191], v[50:53]
	v_mfma_f32_16x16x32_bf16 v[50:53], v[176:179], v[184:187], v[50:53]
	v_mfma_f32_16x16x32_bf16 v[34:37], v[176:179], v[206:209], v[34:37]
	v_mfma_f32_16x16x32_bf16 v[34:37], v[180:183], v[210:213], v[34:37]
	v_mfma_f32_16x16x32_bf16 v[42:45], v[172:175], v[210:213], v[42:45]
	v_mfma_f32_16x16x32_bf16 v[42:45], v[168:171], v[206:209], v[42:45]
	v_mfma_f32_16x16x32_bf16 v[26:29], v[168:171], v[214:217], v[26:29]
	v_mfma_f32_16x16x32_bf16 v[26:29], v[172:175], v[218:221], v[26:29]
	v_mfma_f32_16x16x32_bf16 v[18:21], v[180:183], v[218:221], v[18:21]
	v_mfma_f32_16x16x32_bf16 v[18:21], v[176:179], v[214:217], v[18:21]
	v_mfma_f32_16x16x32_bf16 v[2:5], v[176:179], v[222:225], v[2:5]
	v_mfma_f32_16x16x32_bf16 v[2:5], v[180:183], v[226:229], v[2:5]
	v_mfma_f32_16x16x32_bf16 v[10:13], v[172:175], v[226:229], v[10:13]
	s_barrier
	v_mfma_f32_16x16x32_bf16 v[10:13], v[168:171], v[222:225], v[10:13]
	s_setprio 0
	s_add_i32 s58, 0, 0x18000
	v_add_u32_e32 v145, s58, v142
	s_add_i32 s59, 0, 0x1c000
	ds_read_b128 v[146:149], v145
	ds_read_b128 v[150:153], v145 offset:1024
	ds_read_b128 v[160:163], v145 offset:2048
	ds_read_b128 v[164:167], v145 offset:3072
	v_add_u32_e32 v145, s59, v142
	ds_read_b128 v[168:171], v145
	ds_read_b128 v[172:175], v145 offset:1024
	ds_read_b128 v[176:179], v145 offset:2048
	ds_read_b128 v[180:183], v145 offset:3072
	s_add_u32 s22, s42, 0x40000
	s_addc_u32 s23, s43, 0
	s_mov_b32 m0, s47
	v_lshl_add_u64 v[234:235], s[22:23], 0, v[134:135]
	ds_read_b128 v[184:187], v144 offset:32768
	ds_read_b128 v[188:191], v144 offset:33792
	ds_read_b128 v[206:209], v144 offset:34816
	ds_read_b128 v[210:213], v144 offset:35840
	ds_read_b128 v[214:217], v144 offset:36864
	ds_read_b128 v[218:221], v144 offset:37888
	ds_read_b128 v[222:225], v144 offset:38912
	ds_read_b128 v[226:229], v144 offset:39936
	global_load_lds_dwordx4 v[234:235], off
	v_lshl_add_u64 v[234:235], s[22:23], 0, v[132:133]
	s_mov_b32 m0, s48
	s_nop 0
	global_load_lds_dwordx4 v[234:235], off
	s_waitcnt vmcnt(8)
	s_waitcnt lgkmcnt(0)
	s_barrier
	s_setprio 1
	s_waitcnt lgkmcnt(0)
	v_mfma_f32_16x16x32_bf16 v[126:129], v[146:149], v[184:187], v[126:129]
	v_mfma_f32_16x16x32_bf16 v[126:129], v[150:153], v[188:191], v[126:129]
	v_mfma_f32_16x16x32_bf16 v[118:121], v[164:167], v[188:191], v[118:121]
	v_mfma_f32_16x16x32_bf16 v[118:121], v[160:163], v[184:187], v[118:121]
	v_mfma_f32_16x16x32_bf16 v[102:105], v[160:163], v[206:209], v[102:105]
	v_mfma_f32_16x16x32_bf16 v[102:105], v[164:167], v[210:213], v[102:105]
	v_mfma_f32_16x16x32_bf16 v[110:113], v[150:153], v[210:213], v[110:113]
	v_mfma_f32_16x16x32_bf16 v[110:113], v[146:149], v[206:209], v[110:113]
	v_mfma_f32_16x16x32_bf16 v[94:97], v[146:149], v[214:217], v[94:97]
	v_mfma_f32_16x16x32_bf16 v[94:97], v[150:153], v[218:221], v[94:97]
	v_mfma_f32_16x16x32_bf16 v[86:89], v[164:167], v[218:221], v[86:89]
	v_mfma_f32_16x16x32_bf16 v[86:89], v[160:163], v[214:217], v[86:89]
	v_mfma_f32_16x16x32_bf16 v[70:73], v[160:163], v[222:225], v[70:73]
	v_mfma_f32_16x16x32_bf16 v[70:73], v[164:167], v[226:229], v[70:73]
	v_mfma_f32_16x16x32_bf16 v[78:81], v[150:153], v[226:229], v[78:81]
	v_mfma_f32_16x16x32_bf16 v[78:81], v[146:149], v[222:225], v[78:81]
	s_setprio 0
	s_setprio 1
	v_mfma_f32_16x16x32_bf16 v[122:125], v[168:171], v[184:187], v[122:125]
	v_mfma_f32_16x16x32_bf16 v[122:125], v[172:175], v[188:191], v[122:125]
	v_mfma_f32_16x16x32_bf16 v[114:117], v[180:183], v[188:191], v[114:117]
	v_mfma_f32_16x16x32_bf16 v[114:117], v[176:179], v[184:187], v[114:117]
	v_mfma_f32_16x16x32_bf16 v[98:101], v[176:179], v[206:209], v[98:101]
	v_mfma_f32_16x16x32_bf16 v[98:101], v[180:183], v[210:213], v[98:101]
	v_mfma_f32_16x16x32_bf16 v[106:109], v[172:175], v[210:213], v[106:109]
	v_mfma_f32_16x16x32_bf16 v[106:109], v[168:171], v[206:209], v[106:109]
	v_mfma_f32_16x16x32_bf16 v[90:93], v[168:171], v[214:217], v[90:93]
	v_mfma_f32_16x16x32_bf16 v[90:93], v[172:175], v[218:221], v[90:93]
	v_mfma_f32_16x16x32_bf16 v[82:85], v[180:183], v[218:221], v[82:85]
	v_mfma_f32_16x16x32_bf16 v[82:85], v[176:179], v[214:217], v[82:85]
	v_mfma_f32_16x16x32_bf16 v[66:69], v[176:179], v[222:225], v[66:69]
	v_mfma_f32_16x16x32_bf16 v[66:69], v[180:183], v[226:229], v[66:69]
	v_mfma_f32_16x16x32_bf16 v[74:77], v[172:175], v[226:229], v[74:77]
	s_barrier
; #define PG8_STAGE(bufoff, gbase, voff) do { _Pragma("unroll") for (int _i = 0; _i < 2; ++_i) \
;         __builtin_amdgcn_global_load_lds((const unsigned*)((const char*)(gbase) + (voff)[_i]), (PG8_LAS unsigned*)(lds + (bufoff) + ldsw + _i * 8192), 16, 0, 0); } while (0)
; #define PG8_LDA(dst, b, h) do { _Pragma("unroll") for (int m = 0; m < 4; ++m) _Pragma("unroll") for (int k = 0; k < 2; ++k) dst[m][k] = *(const PG8_LAS bf16x8*)(lds + PG8_SA(b, h) + aoff + m * 2048 + k * 1024); } while (0)
; #define PG8_MMA(ai, bj, At, Bt) do { __builtin_amdgcn_s_setprio(1); _Pragma("unroll") for (int m = 0; m < 4; ++m) _Pragma("unroll") for (int n = 0; n < 2; ++n) _Pragma("unroll") for (int k = 0; k < 2; ++k) \
;         acc[ai][bj][m][n] = __builtin_amdgcn_mfma_f32_16x16x32_bf16(Bt[n][k], At[m][k], acc[ai][bj][m][n], 0, 0, 0); __builtin_amdgcn_s_setprio(0); } while (0)
; #define PG8_WAIT_V(n) asm volatile("s_waitcnt vmcnt(" #n ")" ::: "memory")
; #define PG8_WAIT_L(n) asm volatile("s_waitcnt lgkmcnt(" #n ")" ::: "memory")
; #define PG8_BAR __builtin_amdgcn_s_barrier()
; #define PG8_SCHED __builtin_amdgcn_sched_barrier(0)
; template <class Epi, class Sched, bool ALIGN_EPI = false, bool SP2 = false>
; __device__ __forceinline__ void gemm_phase(PG8_LAS unsigned char* lds, const Gemm g, const Sched& S, const Epi& E) {
;     ...
;             PG8_WAIT_V(8); PG8_WAIT_L(0); PG8_BAR; PG8_MMA(0, 0, At, B0); PG8_MMA(0, 1, At, B1); PG8_BAR; PG8_SCHED;
;             PG8_LDA(At, 1, 1); PG8_STAGE(PG8_SB(1, 0), b3, voffB); PG8_STAGE(PG8_SB(1, 1), b3 + hstep, voffB); PG8_STAGE(PG8_SA(1, 0), a3, voffA);
;             PG8_WAIT_V(8); PG8_WAIT_L(0); PG8_BAR; PG8_MMA(1, 0, At, B0); PG8_MMA(1, 1, At, B1); PG8_BAR; PG8_SCHED;
	v_mfma_f32_16x16x32_bf16 v[74:77], v[168:171], v[222:225], v[74:77]
	s_setprio 0
	s_add_i32 s22, s58, s29
	v_lshl_add_u64 v[230:231], v[230:231], 0, s[38:39]
	s_mov_b32 m0, s22
	ds_read_b128 v[184:187], v144 offset:49152
	ds_read_b128 v[188:191], v144 offset:50176
	ds_read_b128 v[206:209], v144 offset:51200
	ds_read_b128 v[210:213], v144 offset:52224
	ds_read_b128 v[214:217], v144 offset:53248
	ds_read_b128 v[218:221], v144 offset:54272
	ds_read_b128 v[222:225], v144 offset:55296
	ds_read_b128 v[226:229], v144 offset:56320
	global_load_lds_dwordx4 v[230:231], off
	s_add_i32 m0, s22, 0x2000
	s_add_u32 s22, s40, 0x40080
	v_lshl_add_u64 v[230:231], v[232:233], 0, s[38:39]
	s_addc_u32 s23, s41, 0
	s_add_i32 s40, s59, s29
	global_load_lds_dwordx4 v[230:231], off
	v_lshl_add_u64 v[230:231], s[22:23], 0, v[0:1]
	s_mov_b32 m0, s40
	s_nop 0
	global_load_lds_dwordx4 v[230:231], off
	v_lshl_add_u64 v[230:231], s[22:23], 0, v[130:131]
	s_add_i32 m0, s40, 0x2000
	s_nop 0
	global_load_lds_dwordx4 v[230:231], off
	v_lshl_add_u64 v[230:231], s[26:27], 0, v[134:135]
	s_mov_b32 m0, s49
	s_nop 0
	global_load_lds_dwordx4 v[230:231], off
	v_lshl_add_u64 v[230:231], s[26:27], 0, v[132:133]
	s_mov_b32 m0, s50
	s_nop 0
	global_load_lds_dwordx4 v[230:231], off
	s_waitcnt vmcnt(8)
	s_waitcnt lgkmcnt(0)
	s_barrier
	s_setprio 1
	s_waitcnt lgkmcnt(0)
	v_mfma_f32_16x16x32_bf16 v[62:65], v[146:149], v[184:187], v[62:65]
	v_mfma_f32_16x16x32_bf16 v[62:65], v[150:153], v[188:191], v[62:65]
	v_mfma_f32_16x16x32_bf16 v[54:57], v[164:167], v[188:191], v[54:57]
	v_mfma_f32_16x16x32_bf16 v[54:57], v[160:163], v[184:187], v[54:57]
	v_mfma_f32_16x16x32_bf16 v[38:41], v[160:163], v[206:209], v[38:41]
	v_mfma_f32_16x16x32_bf16 v[38:41], v[164:167], v[210:213], v[38:41]
	v_mfma_f32_16x16x32_bf16 v[46:49], v[150:153], v[210:213], v[46:49]
	v_mfma_f32_16x16x32_bf16 v[46:49], v[146:149], v[206:209], v[46:49]
	v_mfma_f32_16x16x32_bf16 v[30:33], v[146:149], v[214:217], v[30:33]
	v_mfma_f32_16x16x32_bf16 v[30:33], v[150:153], v[218:221], v[30:33]
	v_mfma_f32_16x16x32_bf16 v[22:25], v[164:167], v[218:221], v[22:25]
	v_mfma_f32_16x16x32_bf16 v[22:25], v[160:163], v[214:217], v[22:25]
	v_mfma_f32_16x16x32_bf16 v[6:9], v[160:163], v[222:225], v[6:9]
	v_mfma_f32_16x16x32_bf16 v[6:9], v[164:167], v[226:229], v[6:9]
	v_mfma_f32_16x16x32_bf16 v[14:17], v[150:153], v[226:229], v[14:17]
	v_mfma_f32_16x16x32_bf16 v[14:17], v[146:149], v[222:225], v[14:17]
	s_setprio 0
	s_setprio 1
	v_mfma_f32_16x16x32_bf16 v[58:61], v[168:171], v[184:187], v[58:61]
	v_mfma_f32_16x16x32_bf16 v[58:61], v[172:175], v[188:191], v[58:61]
	v_mfma_f32_16x16x32_bf16 v[50:53], v[180:183], v[188:191], v[50:53]
	v_mfma_f32_16x16x32_bf16 v[50:53], v[176:179], v[184:187], v[50:53]
	v_mfma_f32_16x16x32_bf16 v[34:37], v[176:179], v[206:209], v[34:37]
	v_mfma_f32_16x16x32_bf16 v[34:37], v[180:183], v[210:213], v[34:37]
	v_mfma_f32_16x16x32_bf16 v[42:45], v[172:175], v[210:213], v[42:45]
	v_mfma_f32_16x16x32_bf16 v[42:45], v[168:171], v[206:209], v[42:45]
	v_mfma_f32_16x16x32_bf16 v[26:29], v[168:171], v[214:217], v[26:29]
	v_mfma_f32_16x16x32_bf16 v[26:29], v[172:175], v[218:221], v[26:29]
	v_mfma_f32_16x16x32_bf16 v[18:21], v[180:183], v[218:221], v[18:21]
	v_mfma_f32_16x16x32_bf16 v[18:21], v[176:179], v[214:217], v[18:21]
	v_mfma_f32_16x16x32_bf16 v[2:5], v[176:179], v[222:225], v[2:5]
	v_mfma_f32_16x16x32_bf16 v[2:5], v[180:183], v[226:229], v[2:5]
	v_mfma_f32_16x16x32_bf16 v[10:13], v[172:175], v[226:229], v[10:13]
	s_barrier
	v_mfma_f32_16x16x32_bf16 v[10:13], v[168:171], v[222:225], v[10:13]
	s_setprio 0
	s_add_i32 s57, s57, 2
	s_add_u32 s55, s55, 0x100
	s_addc_u32 s56, s56, 0
	s_cmp_gt_u32 s57, 13
	s_mov_b64 s[22:23], s[24:25]
	s_cbranch_scc0 .LBB0_409
	s_and_b64 vcc, exec, s[6:7]
	s_cbranch_vccz .LBB0_412
	s_barrier
